# v28 plus the last pass A accumulator zero-init moved onto its tile-skip path
# baseline (speedup 1.0000x reference)
.LBB0_779:
	v_and_b32_e32 v0, 15, v207
	s_andn2_b64 vcc, exec, s[4:5]
	s_cbranch_vccnz .Lpa_z8
	v_mul_u32_u24_e32 v1, 0x90, v0
	v_add3_u32 v4, s48, v1, v2
	ds_read_b128 v[4:7], v4
	v_add3_u32 v1, 0, v1, v2
	ds_read_b128 v[8:11], v1 offset:4608
	v_mov_b32_e32 v1, v2
	s_waitcnt lgkmcnt(0)
	v_mfma_f32_16x16x32_bf16 v[4:7], v[4:7], v[8:11], 0

.Lpa_z8:
	v_mov_b32_e32 v4, 0
	v_mov_b32_e32 v5, 0
	v_mov_b32_e32 v6, 0
	v_mov_b32_e32 v7, 0
	s_branch .LBB0_781
